# also converted the loop-end grid.sync (20 of 21 grid syncs now use the counter barrier)
# speedup vs baseline: 1.0430x; 1.0021x over previous
; DEVI void sub_barrier(unsigned* ctr, unsigned target) {
;     __threadfence();
;     __syncthreads();
;     if (threadIdx.x == 0) {
;         __threadfence();
;         __hip_atomic_fetch_add(ctr, 1u, __ATOMIC_RELEASE, __HIP_MEMORY_SCOPE_AGENT);
;         while (__hip_atomic_load(ctr, __ATOMIC_ACQUIRE, __HIP_MEMORY_SCOPE_AGENT) < target) __builtin_amdgcn_s_sleep(8);
;         __threadfence();
;     }
;     __syncthreads();
; }
; __global__ void __launch_bounds__(512, 2) fwd_megakernel(Params p) {
;     ...
;         grid.sync();
.LBB0_996:
	v_readlane_b32 s2, v252, 4
	v_readlane_b32 s3, v252, 5
	buffer_wbl2 sc1
	v_mov_b32_e32 v0, 0
	v_mov_b32_e32 v1, 1
	s_nop 3
	s_sub_u32 s10, s2, 8
	s_subb_u32 s11, s3, 0
	s_load_dwordx2 s[8:9], s[10:11], 0x0
	s_load_dword s2, s[10:11], 0x8
	s_waitcnt vmcnt(0) lgkmcnt(0)
	s_add_u32 s8, s8, 0x3a268080
	s_addc_u32 s9, s9, 0
	global_atomic_add v1, v0, v1, s[8:9] sc0
	s_mov_b32 s10, s2
	s_waitcnt vmcnt(0)
	v_readfirstlane_b32 s11, v1
	s_nop 3

; __global__ void __launch_bounds__(512, 2) fwd_megakernel(Params p) {
;     ...
;         grid.sync();
.Lgb10_done:
	s_getpc_b64 s[98:99]
